# WIN (input projection) GEMM epilogue rewritten: row scales hoisted, packed-f32 scaling, batched gelu uniform per tile; on top of SWIGLU epilogue + attention loop changes; numerics unchanged
# speedup vs baseline: 1.0284x; 1.0018x over previous
; __device__ __forceinline__ unsigned cvt_pk_bf16(float lo, float hi) { unsigned r; asm volatile("v_cvt_pk_bf16_f32 %0, %1, %2" : "=v"(r) : "v"(lo), "v"(hi)); return r; }
; __device__ __forceinline__ float sigmoidf_(float x) { return __builtin_amdgcn_rcpf(1.0f + __expf(-x)); }
;     __device__ __forceinline__ float rs_of(int row) const { return __builtin_amdgcn_rsqf(ss_in[row] * (1.0f / DM) + EPS); }
;     __device__ __forceinline__ void operator()(const f32x4 (&acc)[2][2][4][2], const Unit& u, int wr, int wc, int fr, int fq) const {
;     ...
;         } else if constexpr (mode == M_WIN) {
;             const int pn = u.pn;
;             bf16_t* dst; int ld, c0;
;             if (pn < 6) { dst = O0; ld = QKVW; c0 = pn * BM; } else if (pn < 10) { dst = O1; ld = LRUW; c0 = (pn - 6) * BM; } else { dst = O2; ld = LRUW; c0 = (pn - 10) * BM; }
;             const bool act = pn >= 10;
; #pragma unroll
;             for (int ai = 0; ai < 2; ++ai)
; #pragma unroll
;                 for (int m = 0; m < 4; ++m) {
;                     const int row = row0 + ai * HALF + m * 16;
;                     const float s = rs_of(row);
; #pragma unroll
;                     for (int bj = 0; bj < 2; ++bj) {
;                         float v[8];
; #pragma unroll
;                         for (int n = 0; n < 2; ++n)
; #pragma unroll
;                             for (int e = 0; e < 4; ++e) { float x = acc[ai][bj][m][n][e] * s;
;                                 if (act) { const float z = 1.5957691216f * (x + 0.044715f * x * x * x); x = x * sigmoidf_(z); }
;                                 v[4 * n + e] = x; }
;                         u32x4 w; w.x = cvt_pk_bf16(v[0], v[1]); w.y = cvt_pk_bf16(v[2], v[3]); w.z = cvt_pk_bf16(v[4], v[5]); w.w = cvt_pk_bf16(v[6], v[7]);
;                         *(u32x4*)(dst + (size_t)row * ld + c0 + bj * HALF + cw) = w;
;                     }
;                 }
.LBB0_250:
	v_lshl_add_u32 v130, s10, 8, v137
	v_ashrrev_i32_e32 v131, 31, v130
	v_lshl_add_u64 v[132:133], v[130:131], 2, s[54:55]
	global_load_dword v196, v[132:133], off
	global_load_dword v198, v[132:133], off offset:64
	global_load_dword v200, v[132:133], off offset:128
	global_load_dword v202, v[132:133], off offset:192
	global_load_dword v204, v[132:133], off offset:512
	global_load_dword v206, v[132:133], off offset:576
	global_load_dword v208, v[132:133], off offset:640
	global_load_dword v210, v[132:133], off offset:704
	s_ashr_i32 s7, s6, 31
	s_lshl_b64 s[6:7], s[6:7], 1
	s_add_u32 s6, s8, s6
	s_addc_u32 s7, s9, s7
	v_lshl_add_u64 v[180:181], s[6:7], 0, v[186:187]
	v_mad_i64_i32 v[182:183], s[6:7], s4, v130, 0
	v_lshl_add_u64 v[180:181], v[182:183], 1, v[180:181]
	v_mov_b32_e32 v172, 0x3d372713
	v_mov_b32_e32 v174, 0x3fcc422a
	v_mov_b32_e32 v176, 0xbfb8aa3b
	v_mov_b32_e32 v178, 1.0
	s_lshl_b32 s8, s4, 5
	s_mov_b32 s9, 0
	s_mul_i32 s10, s4, 0xa0
	s_mov_b32 s11, 0
	s_cmp_gt_i32 s34, 9
	s_cselect_b64 vcc, -1, 0
	s_waitcnt vmcnt(0)
	v_fmamk_f32 v196, v196, 0x3a000000, v215
	v_fmamk_f32 v198, v198, 0x3a000000, v215
	v_fmamk_f32 v200, v200, 0x3a000000, v215
	v_fmamk_f32 v202, v202, 0x3a000000, v215
	v_fmamk_f32 v204, v204, 0x3a000000, v215
	v_fmamk_f32 v206, v206, 0x3a000000, v215
	v_fmamk_f32 v208, v208, 0x3a000000, v215
	v_fmamk_f32 v210, v210, 0x3a000000, v215
	v_rsq_f32_e32 v196, v196
	v_rsq_f32_e32 v198, v198
	v_rsq_f32_e32 v200, v200
	v_rsq_f32_e32 v202, v202
	v_rsq_f32_e32 v204, v204
	v_rsq_f32_e32 v206, v206
	v_rsq_f32_e32 v208, v208
	v_rsq_f32_e32 v210, v210
	s_nop 0
	v_pk_mul_f32 v[126:127], v[126:127], v[196:197] op_sel_hi:[1,0]
	v_pk_mul_f32 v[128:129], v[128:129], v[196:197] op_sel_hi:[1,0]
	v_pk_mul_f32 v[122:123], v[122:123], v[196:197] op_sel_hi:[1,0]
	v_pk_mul_f32 v[124:125], v[124:125], v[196:197] op_sel_hi:[1,0]
	v_pk_mul_f32 v[118:119], v[118:119], v[196:197] op_sel_hi:[1,0]
	v_pk_mul_f32 v[120:121], v[120:121], v[196:197] op_sel_hi:[1,0]
	v_pk_mul_f32 v[114:115], v[114:115], v[196:197] op_sel_hi:[1,0]
	v_pk_mul_f32 v[116:117], v[116:117], v[196:197] op_sel_hi:[1,0]
	s_cbranch_vccz .Lwin_na0
	v_pk_mul_f32 v[148:149], v[126:127], v[172:173] op_sel_hi:[1,0]
	v_pk_mul_f32 v[150:151], v[128:129], v[172:173] op_sel_hi:[1,0]
	v_pk_mul_f32 v[152:153], v[122:123], v[172:173] op_sel_hi:[1,0]
	v_pk_mul_f32 v[154:155], v[124:125], v[172:173] op_sel_hi:[1,0]
	v_pk_mul_f32 v[148:149], v[126:127], v[148:149]
	v_pk_mul_f32 v[150:151], v[128:129], v[150:151]
	v_pk_mul_f32 v[152:153], v[122:123], v[152:153]
	v_pk_mul_f32 v[154:155], v[124:125], v[154:155]
	v_pk_fma_f32 v[148:149], v[126:127], v[148:149], v[126:127]
	v_pk_fma_f32 v[150:151], v[128:129], v[150:151], v[128:129]
	v_pk_fma_f32 v[152:153], v[122:123], v[152:153], v[122:123]
	v_pk_fma_f32 v[154:155], v[124:125], v[154:155], v[124:125]
	v_pk_mul_f32 v[148:149], v[148:149], v[174:175] op_sel_hi:[1,0]
	v_pk_mul_f32 v[150:151], v[150:151], v[174:175] op_sel_hi:[1,0]
	v_pk_mul_f32 v[152:153], v[152:153], v[174:175] op_sel_hi:[1,0]
	v_pk_mul_f32 v[154:155], v[154:155], v[174:175] op_sel_hi:[1,0]
	v_pk_mul_f32 v[148:149], v[148:149], v[176:177] op_sel_hi:[1,0]
	v_pk_mul_f32 v[150:151], v[150:151], v[176:177] op_sel_hi:[1,0]
	v_pk_mul_f32 v[152:153], v[152:153], v[176:177] op_sel_hi:[1,0]
	v_pk_mul_f32 v[154:155], v[154:155], v[176:177] op_sel_hi:[1,0]
	v_exp_f32_e32 v148, v148
	v_exp_f32_e32 v149, v149
	v_exp_f32_e32 v150, v150
	v_exp_f32_e32 v151, v151
	v_exp_f32_e32 v152, v152
	v_exp_f32_e32 v153, v153
	v_exp_f32_e32 v154, v154
	v_exp_f32_e32 v155, v155
	s_nop 0
	v_pk_add_f32 v[148:149], v[148:149], v[178:179] op_sel_hi:[1,0]
	v_pk_add_f32 v[150:151], v[150:151], v[178:179] op_sel_hi:[1,0]
	v_pk_add_f32 v[152:153], v[152:153], v[178:179] op_sel_hi:[1,0]
	v_pk_add_f32 v[154:155], v[154:155], v[178:179] op_sel_hi:[1,0]
	v_rcp_f32_e32 v148, v148
	v_rcp_f32_e32 v149, v149
	v_rcp_f32_e32 v150, v150
	v_rcp_f32_e32 v151, v151
	v_rcp_f32_e32 v152, v152
	v_rcp_f32_e32 v153, v153
	v_rcp_f32_e32 v154, v154
	v_rcp_f32_e32 v155, v155
	s_nop 0
	v_pk_mul_f32 v[126:127], v[126:127], v[148:149]
	v_pk_mul_f32 v[128:129], v[128:129], v[150:151]
	v_pk_mul_f32 v[122:123], v[122:123], v[152:153]
	v_pk_mul_f32 v[124:125], v[124:125], v[154:155]
	v_pk_mul_f32 v[148:149], v[118:119], v[172:173] op_sel_hi:[1,0]
	v_pk_mul_f32 v[150:151], v[120:121], v[172:173] op_sel_hi:[1,0]
	v_pk_mul_f32 v[152:153], v[114:115], v[172:173] op_sel_hi:[1,0]
	v_pk_mul_f32 v[154:155], v[116:117], v[172:173] op_sel_hi:[1,0]
	v_pk_mul_f32 v[148:149], v[118:119], v[148:149]
	v_pk_mul_f32 v[150:151], v[120:121], v[150:151]
	v_pk_mul_f32 v[152:153], v[114:115], v[152:153]
	v_pk_mul_f32 v[154:155], v[116:117], v[154:155]
	v_pk_fma_f32 v[148:149], v[118:119], v[148:149], v[118:119]
	v_pk_fma_f32 v[150:151], v[120:121], v[150:151], v[120:121]
	v_pk_fma_f32 v[152:153], v[114:115], v[152:153], v[114:115]
	v_pk_fma_f32 v[154:155], v[116:117], v[154:155], v[116:117]
	v_pk_mul_f32 v[148:149], v[148:149], v[174:175] op_sel_hi:[1,0]
	v_pk_mul_f32 v[150:151], v[150:151], v[174:175] op_sel_hi:[1,0]
	v_pk_mul_f32 v[152:153], v[152:153], v[174:175] op_sel_hi:[1,0]
	v_pk_mul_f32 v[154:155], v[154:155], v[174:175] op_sel_hi:[1,0]
	v_pk_mul_f32 v[148:149], v[148:149], v[176:177] op_sel_hi:[1,0]
	v_pk_mul_f32 v[150:151], v[150:151], v[176:177] op_sel_hi:[1,0]
	v_pk_mul_f32 v[152:153], v[152:153], v[176:177] op_sel_hi:[1,0]
	v_pk_mul_f32 v[154:155], v[154:155], v[176:177] op_sel_hi:[1,0]
	v_exp_f32_e32 v148, v148
	v_exp_f32_e32 v149, v149
	v_exp_f32_e32 v150, v150
	v_exp_f32_e32 v151, v151
	v_exp_f32_e32 v152, v152
	v_exp_f32_e32 v153, v153
	v_exp_f32_e32 v154, v154
	v_exp_f32_e32 v155, v155
	s_nop 0
	v_pk_add_f32 v[148:149], v[148:149], v[178:179] op_sel_hi:[1,0]
	v_pk_add_f32 v[150:151], v[150:151], v[178:179] op_sel_hi:[1,0]
	v_pk_add_f32 v[152:153], v[152:153], v[178:179] op_sel_hi:[1,0]
	v_pk_add_f32 v[154:155], v[154:155], v[178:179] op_sel_hi:[1,0]
	v_rcp_f32_e32 v148, v148
	v_rcp_f32_e32 v149, v149
	v_rcp_f32_e32 v150, v150
	v_rcp_f32_e32 v151, v151
	v_rcp_f32_e32 v152, v152
	v_rcp_f32_e32 v153, v153
	v_rcp_f32_e32 v154, v154
	v_rcp_f32_e32 v155, v155
	s_nop 0
	v_pk_mul_f32 v[118:119], v[118:119], v[148:149]
	v_pk_mul_f32 v[120:121], v[120:121], v[150:151]
	v_pk_mul_f32 v[114:115], v[114:115], v[152:153]
	v_pk_mul_f32 v[116:117], v[116:117], v[154:155]
; __device__ __forceinline__ unsigned cvt_pk_bf16(float lo, float hi) { unsigned r; asm volatile("v_cvt_pk_bf16_f32 %0, %1, %2" : "=v"(r) : "v"(lo), "v"(hi)); return r; }
; __device__ __forceinline__ float sigmoidf_(float x) { return __builtin_amdgcn_rcpf(1.0f + __expf(-x)); }
;     __device__ __forceinline__ float rs_of(int row) const { return __builtin_amdgcn_rsqf(ss_in[row] * (1.0f / DM) + EPS); }
;     __device__ __forceinline__ void operator()(const f32x4 (&acc)[2][2][4][2], const Unit& u, int wr, int wc, int fr, int fq) const {
;     ...
; #pragma unroll
;             for (int ai = 0; ai < 2; ++ai)
; #pragma unroll
;                 for (int m = 0; m < 4; ++m) {
;                     const int row = row0 + ai * HALF + m * 16;
;                     const float s = rs_of(row);
; #pragma unroll
;                     for (int bj = 0; bj < 2; ++bj) {
;                         float v[8];
; #pragma unroll
;                         for (int n = 0; n < 2; ++n)
; #pragma unroll
;                             for (int e = 0; e < 4; ++e) { float x = acc[ai][bj][m][n][e] * s;
;                                 if (act) { const float z = 1.5957691216f * (x + 0.044715f * x * x * x); x = x * sigmoidf_(z); }
;                                 v[4 * n + e] = x; }
;                         u32x4 w; w.x = cvt_pk_bf16(v[0], v[1]); w.y = cvt_pk_bf16(v[2], v[3]); w.z = cvt_pk_bf16(v[4], v[5]); w.w = cvt_pk_bf16(v[6], v[7]);
;                         *(u32x4*)(dst + (size_t)row * ld + c0 + bj * HALF + cw) = w;
;                     }
;                 }
.Lwin_na0:
	v_cvt_pk_bf16_f32 v126, v126, v127
	v_cvt_pk_bf16_f32 v127, v128, v129
	v_cvt_pk_bf16_f32 v128, v122, v123
	v_cvt_pk_bf16_f32 v129, v124, v125
	v_cvt_pk_bf16_f32 v118, v118, v119
	v_cvt_pk_bf16_f32 v119, v120, v121
	v_cvt_pk_bf16_f32 v120, v114, v115
	v_cvt_pk_bf16_f32 v121, v116, v117
	global_store_dwordx4 v[180:181], v[126:129], off
	global_store_dwordx4 v[180:181], v[118:121], off offset:256
	v_lshl_add_u64 v[180:181], v[180:181], 0, s[8:9]
	v_pk_mul_f32 v[110:111], v[110:111], v[198:199] op_sel_hi:[1,0]
	v_pk_mul_f32 v[112:113], v[112:113], v[198:199] op_sel_hi:[1,0]
	v_pk_mul_f32 v[106:107], v[106:107], v[198:199] op_sel_hi:[1,0]
	v_pk_mul_f32 v[108:109], v[108:109], v[198:199] op_sel_hi:[1,0]
	v_pk_mul_f32 v[102:103], v[102:103], v[198:199] op_sel_hi:[1,0]
	v_pk_mul_f32 v[104:105], v[104:105], v[198:199] op_sel_hi:[1,0]
	v_pk_mul_f32 v[98:99], v[98:99], v[198:199] op_sel_hi:[1,0]
	v_pk_mul_f32 v[100:101], v[100:101], v[198:199] op_sel_hi:[1,0]
	s_cbranch_vccz .Lwin_na1
	v_pk_mul_f32 v[148:149], v[110:111], v[172:173] op_sel_hi:[1,0]
	v_pk_mul_f32 v[150:151], v[112:113], v[172:173] op_sel_hi:[1,0]
	v_pk_mul_f32 v[152:153], v[106:107], v[172:173] op_sel_hi:[1,0]
	v_pk_mul_f32 v[154:155], v[108:109], v[172:173] op_sel_hi:[1,0]
	v_pk_mul_f32 v[148:149], v[110:111], v[148:149]
	v_pk_mul_f32 v[150:151], v[112:113], v[150:151]
	v_pk_mul_f32 v[152:153], v[106:107], v[152:153]
	v_pk_mul_f32 v[154:155], v[108:109], v[154:155]
	v_pk_fma_f32 v[148:149], v[110:111], v[148:149], v[110:111]
	v_pk_fma_f32 v[150:151], v[112:113], v[150:151], v[112:113]
	v_pk_fma_f32 v[152:153], v[106:107], v[152:153], v[106:107]
	v_pk_fma_f32 v[154:155], v[108:109], v[154:155], v[108:109]
	v_pk_mul_f32 v[148:149], v[148:149], v[174:175] op_sel_hi:[1,0]
	v_pk_mul_f32 v[150:151], v[150:151], v[174:175] op_sel_hi:[1,0]
	v_pk_mul_f32 v[152:153], v[152:153], v[174:175] op_sel_hi:[1,0]
	v_pk_mul_f32 v[154:155], v[154:155], v[174:175] op_sel_hi:[1,0]
	v_pk_mul_f32 v[148:149], v[148:149], v[176:177] op_sel_hi:[1,0]
	v_pk_mul_f32 v[150:151], v[150:151], v[176:177] op_sel_hi:[1,0]
	v_pk_mul_f32 v[152:153], v[152:153], v[176:177] op_sel_hi:[1,0]
	v_pk_mul_f32 v[154:155], v[154:155], v[176:177] op_sel_hi:[1,0]
	v_exp_f32_e32 v148, v148
	v_exp_f32_e32 v149, v149
	v_exp_f32_e32 v150, v150
	v_exp_f32_e32 v151, v151
	v_exp_f32_e32 v152, v152
	v_exp_f32_e32 v153, v153
	v_exp_f32_e32 v154, v154
	v_exp_f32_e32 v155, v155
	s_nop 0
	v_pk_add_f32 v[148:149], v[148:149], v[178:179] op_sel_hi:[1,0]
	v_pk_add_f32 v[150:151], v[150:151], v[178:179] op_sel_hi:[1,0]
	v_pk_add_f32 v[152:153], v[152:153], v[178:179] op_sel_hi:[1,0]
	v_pk_add_f32 v[154:155], v[154:155], v[178:179] op_sel_hi:[1,0]
	v_rcp_f32_e32 v148, v148
	v_rcp_f32_e32 v149, v149
	v_rcp_f32_e32 v150, v150
	v_rcp_f32_e32 v151, v151
	v_rcp_f32_e32 v152, v152
	v_rcp_f32_e32 v153, v153
	v_rcp_f32_e32 v154, v154
	v_rcp_f32_e32 v155, v155
	s_nop 0
	v_pk_mul_f32 v[110:111], v[110:111], v[148:149]
	v_pk_mul_f32 v[112:113], v[112:113], v[150:151]
	v_pk_mul_f32 v[106:107], v[106:107], v[152:153]
	v_pk_mul_f32 v[108:109], v[108:109], v[154:155]
	v_pk_mul_f32 v[148:149], v[102:103], v[172:173] op_sel_hi:[1,0]
	v_pk_mul_f32 v[150:151], v[104:105], v[172:173] op_sel_hi:[1,0]
	v_pk_mul_f32 v[152:153], v[98:99], v[172:173] op_sel_hi:[1,0]
	v_pk_mul_f32 v[154:155], v[100:101], v[172:173] op_sel_hi:[1,0]
	v_pk_mul_f32 v[148:149], v[102:103], v[148:149]
	v_pk_mul_f32 v[150:151], v[104:105], v[150:151]
	v_pk_mul_f32 v[152:153], v[98:99], v[152:153]
	v_pk_mul_f32 v[154:155], v[100:101], v[154:155]
	v_pk_fma_f32 v[148:149], v[102:103], v[148:149], v[102:103]
	v_pk_fma_f32 v[150:151], v[104:105], v[150:151], v[104:105]
	v_pk_fma_f32 v[152:153], v[98:99], v[152:153], v[98:99]
	v_pk_fma_f32 v[154:155], v[100:101], v[154:155], v[100:101]
	v_pk_mul_f32 v[148:149], v[148:149], v[174:175] op_sel_hi:[1,0]
	v_pk_mul_f32 v[150:151], v[150:151], v[174:175] op_sel_hi:[1,0]
	v_pk_mul_f32 v[152:153], v[152:153], v[174:175] op_sel_hi:[1,0]
	v_pk_mul_f32 v[154:155], v[154:155], v[174:175] op_sel_hi:[1,0]
	v_pk_mul_f32 v[148:149], v[148:149], v[176:177] op_sel_hi:[1,0]
	v_pk_mul_f32 v[150:151], v[150:151], v[176:177] op_sel_hi:[1,0]
	v_pk_mul_f32 v[152:153], v[152:153], v[176:177] op_sel_hi:[1,0]
	v_pk_mul_f32 v[154:155], v[154:155], v[176:177] op_sel_hi:[1,0]
	v_exp_f32_e32 v148, v148
	v_exp_f32_e32 v149, v149
	v_exp_f32_e32 v150, v150
	v_exp_f32_e32 v151, v151
	v_exp_f32_e32 v152, v152
	v_exp_f32_e32 v153, v153
	v_exp_f32_e32 v154, v154
	v_exp_f32_e32 v155, v155
	s_nop 0
	v_pk_add_f32 v[148:149], v[148:149], v[178:179] op_sel_hi:[1,0]
	v_pk_add_f32 v[150:151], v[150:151], v[178:179] op_sel_hi:[1,0]
	v_pk_add_f32 v[152:153], v[152:153], v[178:179] op_sel_hi:[1,0]
	v_pk_add_f32 v[154:155], v[154:155], v[178:179] op_sel_hi:[1,0]
	v_rcp_f32_e32 v148, v148
	v_rcp_f32_e32 v149, v149
	v_rcp_f32_e32 v150, v150
	v_rcp_f32_e32 v151, v151
	v_rcp_f32_e32 v152, v152
	v_rcp_f32_e32 v153, v153
	v_rcp_f32_e32 v154, v154
	v_rcp_f32_e32 v155, v155
	s_nop 0
	v_pk_mul_f32 v[102:103], v[102:103], v[148:149]
	v_pk_mul_f32 v[104:105], v[104:105], v[150:151]
	v_pk_mul_f32 v[98:99], v[98:99], v[152:153]
	v_pk_mul_f32 v[100:101], v[100:101], v[154:155]
; __device__ __forceinline__ unsigned cvt_pk_bf16(float lo, float hi) { unsigned r; asm volatile("v_cvt_pk_bf16_f32 %0, %1, %2" : "=v"(r) : "v"(lo), "v"(hi)); return r; }
; __device__ __forceinline__ float sigmoidf_(float x) { return __builtin_amdgcn_rcpf(1.0f + __expf(-x)); }
;     __device__ __forceinline__ float rs_of(int row) const { return __builtin_amdgcn_rsqf(ss_in[row] * (1.0f / DM) + EPS); }
;     __device__ __forceinline__ void operator()(const f32x4 (&acc)[2][2][4][2], const Unit& u, int wr, int wc, int fr, int fq) const {
;     ...
; #pragma unroll
;             for (int ai = 0; ai < 2; ++ai)
; #pragma unroll
;                 for (int m = 0; m < 4; ++m) {
;                     const int row = row0 + ai * HALF + m * 16;
;                     const float s = rs_of(row);
; #pragma unroll
;                     for (int bj = 0; bj < 2; ++bj) {
;                         float v[8];
; #pragma unroll
;                         for (int n = 0; n < 2; ++n)
; #pragma unroll
;                             for (int e = 0; e < 4; ++e) { float x = acc[ai][bj][m][n][e] * s;
;                                 if (act) { const float z = 1.5957691216f * (x + 0.044715f * x * x * x); x = x * sigmoidf_(z); }
;                                 v[4 * n + e] = x; }
;                         u32x4 w; w.x = cvt_pk_bf16(v[0], v[1]); w.y = cvt_pk_bf16(v[2], v[3]); w.z = cvt_pk_bf16(v[4], v[5]); w.w = cvt_pk_bf16(v[6], v[7]);
;                         *(u32x4*)(dst + (size_t)row * ld + c0 + bj * HALF + cw) = w;
;                     }
;                 }
.Lwin_na1:
	v_cvt_pk_bf16_f32 v110, v110, v111
	v_cvt_pk_bf16_f32 v111, v112, v113
	v_cvt_pk_bf16_f32 v112, v106, v107
	v_cvt_pk_bf16_f32 v113, v108, v109
	v_cvt_pk_bf16_f32 v102, v102, v103
	v_cvt_pk_bf16_f32 v103, v104, v105
	v_cvt_pk_bf16_f32 v104, v98, v99
	v_cvt_pk_bf16_f32 v105, v100, v101
	global_store_dwordx4 v[180:181], v[110:113], off
	global_store_dwordx4 v[180:181], v[102:105], off offset:256
	v_lshl_add_u64 v[180:181], v[180:181], 0, s[8:9]
	v_pk_mul_f32 v[94:95], v[94:95], v[200:201] op_sel_hi:[1,0]
	v_pk_mul_f32 v[96:97], v[96:97], v[200:201] op_sel_hi:[1,0]
	v_pk_mul_f32 v[90:91], v[90:91], v[200:201] op_sel_hi:[1,0]
	v_pk_mul_f32 v[92:93], v[92:93], v[200:201] op_sel_hi:[1,0]
	v_pk_mul_f32 v[86:87], v[86:87], v[200:201] op_sel_hi:[1,0]
	v_pk_mul_f32 v[88:89], v[88:89], v[200:201] op_sel_hi:[1,0]
	v_pk_mul_f32 v[82:83], v[82:83], v[200:201] op_sel_hi:[1,0]
	v_pk_mul_f32 v[84:85], v[84:85], v[200:201] op_sel_hi:[1,0]
	s_cbranch_vccz .Lwin_na2
	v_pk_mul_f32 v[148:149], v[94:95], v[172:173] op_sel_hi:[1,0]
	v_pk_mul_f32 v[150:151], v[96:97], v[172:173] op_sel_hi:[1,0]
	v_pk_mul_f32 v[152:153], v[90:91], v[172:173] op_sel_hi:[1,0]
	v_pk_mul_f32 v[154:155], v[92:93], v[172:173] op_sel_hi:[1,0]
	v_pk_mul_f32 v[148:149], v[94:95], v[148:149]
	v_pk_mul_f32 v[150:151], v[96:97], v[150:151]
	v_pk_mul_f32 v[152:153], v[90:91], v[152:153]
	v_pk_mul_f32 v[154:155], v[92:93], v[154:155]
	v_pk_fma_f32 v[148:149], v[94:95], v[148:149], v[94:95]
	v_pk_fma_f32 v[150:151], v[96:97], v[150:151], v[96:97]
	v_pk_fma_f32 v[152:153], v[90:91], v[152:153], v[90:91]
	v_pk_fma_f32 v[154:155], v[92:93], v[154:155], v[92:93]
	v_pk_mul_f32 v[148:149], v[148:149], v[174:175] op_sel_hi:[1,0]
	v_pk_mul_f32 v[150:151], v[150:151], v[174:175] op_sel_hi:[1,0]
	v_pk_mul_f32 v[152:153], v[152:153], v[174:175] op_sel_hi:[1,0]
	v_pk_mul_f32 v[154:155], v[154:155], v[174:175] op_sel_hi:[1,0]
	v_pk_mul_f32 v[148:149], v[148:149], v[176:177] op_sel_hi:[1,0]
	v_pk_mul_f32 v[150:151], v[150:151], v[176:177] op_sel_hi:[1,0]
	v_pk_mul_f32 v[152:153], v[152:153], v[176:177] op_sel_hi:[1,0]
	v_pk_mul_f32 v[154:155], v[154:155], v[176:177] op_sel_hi:[1,0]
	v_exp_f32_e32 v148, v148
	v_exp_f32_e32 v149, v149
	v_exp_f32_e32 v150, v150
	v_exp_f32_e32 v151, v151
	v_exp_f32_e32 v152, v152
	v_exp_f32_e32 v153, v153
	v_exp_f32_e32 v154, v154
	v_exp_f32_e32 v155, v155
	s_nop 0
	v_pk_add_f32 v[148:149], v[148:149], v[178:179] op_sel_hi:[1,0]
	v_pk_add_f32 v[150:151], v[150:151], v[178:179] op_sel_hi:[1,0]
	v_pk_add_f32 v[152:153], v[152:153], v[178:179] op_sel_hi:[1,0]
	v_pk_add_f32 v[154:155], v[154:155], v[178:179] op_sel_hi:[1,0]
	v_rcp_f32_e32 v148, v148
	v_rcp_f32_e32 v149, v149
	v_rcp_f32_e32 v150, v150
	v_rcp_f32_e32 v151, v151
	v_rcp_f32_e32 v152, v152
	v_rcp_f32_e32 v153, v153
	v_rcp_f32_e32 v154, v154
	v_rcp_f32_e32 v155, v155
	s_nop 0
	v_pk_mul_f32 v[94:95], v[94:95], v[148:149]
	v_pk_mul_f32 v[96:97], v[96:97], v[150:151]
	v_pk_mul_f32 v[90:91], v[90:91], v[152:153]
	v_pk_mul_f32 v[92:93], v[92:93], v[154:155]
	v_pk_mul_f32 v[148:149], v[86:87], v[172:173] op_sel_hi:[1,0]
	v_pk_mul_f32 v[150:151], v[88:89], v[172:173] op_sel_hi:[1,0]
	v_pk_mul_f32 v[152:153], v[82:83], v[172:173] op_sel_hi:[1,0]
	v_pk_mul_f32 v[154:155], v[84:85], v[172:173] op_sel_hi:[1,0]
	v_pk_mul_f32 v[148:149], v[86:87], v[148:149]
	v_pk_mul_f32 v[150:151], v[88:89], v[150:151]
	v_pk_mul_f32 v[152:153], v[82:83], v[152:153]
	v_pk_mul_f32 v[154:155], v[84:85], v[154:155]
	v_pk_fma_f32 v[148:149], v[86:87], v[148:149], v[86:87]
	v_pk_fma_f32 v[150:151], v[88:89], v[150:151], v[88:89]
	v_pk_fma_f32 v[152:153], v[82:83], v[152:153], v[82:83]
	v_pk_fma_f32 v[154:155], v[84:85], v[154:155], v[84:85]
	v_pk_mul_f32 v[148:149], v[148:149], v[174:175] op_sel_hi:[1,0]
	v_pk_mul_f32 v[150:151], v[150:151], v[174:175] op_sel_hi:[1,0]
	v_pk_mul_f32 v[152:153], v[152:153], v[174:175] op_sel_hi:[1,0]
	v_pk_mul_f32 v[154:155], v[154:155], v[174:175] op_sel_hi:[1,0]
	v_pk_mul_f32 v[148:149], v[148:149], v[176:177] op_sel_hi:[1,0]
	v_pk_mul_f32 v[150:151], v[150:151], v[176:177] op_sel_hi:[1,0]
	v_pk_mul_f32 v[152:153], v[152:153], v[176:177] op_sel_hi:[1,0]
	v_pk_mul_f32 v[154:155], v[154:155], v[176:177] op_sel_hi:[1,0]
	v_exp_f32_e32 v148, v148
	v_exp_f32_e32 v149, v149
	v_exp_f32_e32 v150, v150
	v_exp_f32_e32 v151, v151
	v_exp_f32_e32 v152, v152
	v_exp_f32_e32 v153, v153
	v_exp_f32_e32 v154, v154
	v_exp_f32_e32 v155, v155
	s_nop 0
	v_pk_add_f32 v[148:149], v[148:149], v[178:179] op_sel_hi:[1,0]
	v_pk_add_f32 v[150:151], v[150:151], v[178:179] op_sel_hi:[1,0]
	v_pk_add_f32 v[152:153], v[152:153], v[178:179] op_sel_hi:[1,0]
	v_pk_add_f32 v[154:155], v[154:155], v[178:179] op_sel_hi:[1,0]
	v_rcp_f32_e32 v148, v148
	v_rcp_f32_e32 v149, v149
	v_rcp_f32_e32 v150, v150
	v_rcp_f32_e32 v151, v151
	v_rcp_f32_e32 v152, v152
	v_rcp_f32_e32 v153, v153
	v_rcp_f32_e32 v154, v154
	v_rcp_f32_e32 v155, v155
	s_nop 0
	v_pk_mul_f32 v[86:87], v[86:87], v[148:149]
	v_pk_mul_f32 v[88:89], v[88:89], v[150:151]
	v_pk_mul_f32 v[82:83], v[82:83], v[152:153]
	v_pk_mul_f32 v[84:85], v[84:85], v[154:155]
; __device__ __forceinline__ unsigned cvt_pk_bf16(float lo, float hi) { unsigned r; asm volatile("v_cvt_pk_bf16_f32 %0, %1, %2" : "=v"(r) : "v"(lo), "v"(hi)); return r; }
; __device__ __forceinline__ float sigmoidf_(float x) { return __builtin_amdgcn_rcpf(1.0f + __expf(-x)); }
;     __device__ __forceinline__ float rs_of(int row) const { return __builtin_amdgcn_rsqf(ss_in[row] * (1.0f / DM) + EPS); }
;     __device__ __forceinline__ void operator()(const f32x4 (&acc)[2][2][4][2], const Unit& u, int wr, int wc, int fr, int fq) const {
;     ...
; #pragma unroll
;             for (int ai = 0; ai < 2; ++ai)
; #pragma unroll
;                 for (int m = 0; m < 4; ++m) {
;                     const int row = row0 + ai * HALF + m * 16;
;                     const float s = rs_of(row);
; #pragma unroll
;                     for (int bj = 0; bj < 2; ++bj) {
;                         float v[8];
; #pragma unroll
;                         for (int n = 0; n < 2; ++n)
; #pragma unroll
;                             for (int e = 0; e < 4; ++e) { float x = acc[ai][bj][m][n][e] * s;
;                                 if (act) { const float z = 1.5957691216f * (x + 0.044715f * x * x * x); x = x * sigmoidf_(z); }
;                                 v[4 * n + e] = x; }
;                         u32x4 w; w.x = cvt_pk_bf16(v[0], v[1]); w.y = cvt_pk_bf16(v[2], v[3]); w.z = cvt_pk_bf16(v[4], v[5]); w.w = cvt_pk_bf16(v[6], v[7]);
;                         *(u32x4*)(dst + (size_t)row * ld + c0 + bj * HALF + cw) = w;
;                     }
;                 }
.Lwin_na2:
	v_cvt_pk_bf16_f32 v94, v94, v95
	v_cvt_pk_bf16_f32 v95, v96, v97
	v_cvt_pk_bf16_f32 v96, v90, v91
	v_cvt_pk_bf16_f32 v97, v92, v93
	v_cvt_pk_bf16_f32 v86, v86, v87
	v_cvt_pk_bf16_f32 v87, v88, v89
	v_cvt_pk_bf16_f32 v88, v82, v83
	v_cvt_pk_bf16_f32 v89, v84, v85
	global_store_dwordx4 v[180:181], v[94:97], off
	global_store_dwordx4 v[180:181], v[86:89], off offset:256
	v_lshl_add_u64 v[180:181], v[180:181], 0, s[8:9]
	v_pk_mul_f32 v[78:79], v[78:79], v[202:203] op_sel_hi:[1,0]
	v_pk_mul_f32 v[80:81], v[80:81], v[202:203] op_sel_hi:[1,0]
	v_pk_mul_f32 v[74:75], v[74:75], v[202:203] op_sel_hi:[1,0]
	v_pk_mul_f32 v[76:77], v[76:77], v[202:203] op_sel_hi:[1,0]
	v_pk_mul_f32 v[70:71], v[70:71], v[202:203] op_sel_hi:[1,0]
	v_pk_mul_f32 v[72:73], v[72:73], v[202:203] op_sel_hi:[1,0]
	v_pk_mul_f32 v[66:67], v[66:67], v[202:203] op_sel_hi:[1,0]
	v_pk_mul_f32 v[68:69], v[68:69], v[202:203] op_sel_hi:[1,0]
	s_cbranch_vccz .Lwin_na3
	v_pk_mul_f32 v[148:149], v[78:79], v[172:173] op_sel_hi:[1,0]
	v_pk_mul_f32 v[150:151], v[80:81], v[172:173] op_sel_hi:[1,0]
	v_pk_mul_f32 v[152:153], v[74:75], v[172:173] op_sel_hi:[1,0]
	v_pk_mul_f32 v[154:155], v[76:77], v[172:173] op_sel_hi:[1,0]
	v_pk_mul_f32 v[148:149], v[78:79], v[148:149]
	v_pk_mul_f32 v[150:151], v[80:81], v[150:151]
	v_pk_mul_f32 v[152:153], v[74:75], v[152:153]
	v_pk_mul_f32 v[154:155], v[76:77], v[154:155]
	v_pk_fma_f32 v[148:149], v[78:79], v[148:149], v[78:79]
	v_pk_fma_f32 v[150:151], v[80:81], v[150:151], v[80:81]
	v_pk_fma_f32 v[152:153], v[74:75], v[152:153], v[74:75]
	v_pk_fma_f32 v[154:155], v[76:77], v[154:155], v[76:77]
	v_pk_mul_f32 v[148:149], v[148:149], v[174:175] op_sel_hi:[1,0]
	v_pk_mul_f32 v[150:151], v[150:151], v[174:175] op_sel_hi:[1,0]
	v_pk_mul_f32 v[152:153], v[152:153], v[174:175] op_sel_hi:[1,0]
	v_pk_mul_f32 v[154:155], v[154:155], v[174:175] op_sel_hi:[1,0]
	v_pk_mul_f32 v[148:149], v[148:149], v[176:177] op_sel_hi:[1,0]
	v_pk_mul_f32 v[150:151], v[150:151], v[176:177] op_sel_hi:[1,0]
	v_pk_mul_f32 v[152:153], v[152:153], v[176:177] op_sel_hi:[1,0]
	v_pk_mul_f32 v[154:155], v[154:155], v[176:177] op_sel_hi:[1,0]
	v_exp_f32_e32 v148, v148
	v_exp_f32_e32 v149, v149
	v_exp_f32_e32 v150, v150
	v_exp_f32_e32 v151, v151
	v_exp_f32_e32 v152, v152
	v_exp_f32_e32 v153, v153
	v_exp_f32_e32 v154, v154
	v_exp_f32_e32 v155, v155
	s_nop 0
	v_pk_add_f32 v[148:149], v[148:149], v[178:179] op_sel_hi:[1,0]
	v_pk_add_f32 v[150:151], v[150:151], v[178:179] op_sel_hi:[1,0]
	v_pk_add_f32 v[152:153], v[152:153], v[178:179] op_sel_hi:[1,0]
	v_pk_add_f32 v[154:155], v[154:155], v[178:179] op_sel_hi:[1,0]
	v_rcp_f32_e32 v148, v148
	v_rcp_f32_e32 v149, v149
	v_rcp_f32_e32 v150, v150
	v_rcp_f32_e32 v151, v151
	v_rcp_f32_e32 v152, v152
	v_rcp_f32_e32 v153, v153
	v_rcp_f32_e32 v154, v154
	v_rcp_f32_e32 v155, v155
	s_nop 0
	v_pk_mul_f32 v[78:79], v[78:79], v[148:149]
	v_pk_mul_f32 v[80:81], v[80:81], v[150:151]
	v_pk_mul_f32 v[74:75], v[74:75], v[152:153]
	v_pk_mul_f32 v[76:77], v[76:77], v[154:155]
	v_pk_mul_f32 v[148:149], v[70:71], v[172:173] op_sel_hi:[1,0]
	v_pk_mul_f32 v[150:151], v[72:73], v[172:173] op_sel_hi:[1,0]
	v_pk_mul_f32 v[152:153], v[66:67], v[172:173] op_sel_hi:[1,0]
	v_pk_mul_f32 v[154:155], v[68:69], v[172:173] op_sel_hi:[1,0]
	v_pk_mul_f32 v[148:149], v[70:71], v[148:149]
	v_pk_mul_f32 v[150:151], v[72:73], v[150:151]
	v_pk_mul_f32 v[152:153], v[66:67], v[152:153]
	v_pk_mul_f32 v[154:155], v[68:69], v[154:155]
	v_pk_fma_f32 v[148:149], v[70:71], v[148:149], v[70:71]
	v_pk_fma_f32 v[150:151], v[72:73], v[150:151], v[72:73]
	v_pk_fma_f32 v[152:153], v[66:67], v[152:153], v[66:67]
	v_pk_fma_f32 v[154:155], v[68:69], v[154:155], v[68:69]
	v_pk_mul_f32 v[148:149], v[148:149], v[174:175] op_sel_hi:[1,0]
	v_pk_mul_f32 v[150:151], v[150:151], v[174:175] op_sel_hi:[1,0]
	v_pk_mul_f32 v[152:153], v[152:153], v[174:175] op_sel_hi:[1,0]
	v_pk_mul_f32 v[154:155], v[154:155], v[174:175] op_sel_hi:[1,0]
	v_pk_mul_f32 v[148:149], v[148:149], v[176:177] op_sel_hi:[1,0]
	v_pk_mul_f32 v[150:151], v[150:151], v[176:177] op_sel_hi:[1,0]
	v_pk_mul_f32 v[152:153], v[152:153], v[176:177] op_sel_hi:[1,0]
	v_pk_mul_f32 v[154:155], v[154:155], v[176:177] op_sel_hi:[1,0]
	v_exp_f32_e32 v148, v148
	v_exp_f32_e32 v149, v149
	v_exp_f32_e32 v150, v150
	v_exp_f32_e32 v151, v151
	v_exp_f32_e32 v152, v152
	v_exp_f32_e32 v153, v153
	v_exp_f32_e32 v154, v154
	v_exp_f32_e32 v155, v155
	s_nop 0
	v_pk_add_f32 v[148:149], v[148:149], v[178:179] op_sel_hi:[1,0]
	v_pk_add_f32 v[150:151], v[150:151], v[178:179] op_sel_hi:[1,0]
	v_pk_add_f32 v[152:153], v[152:153], v[178:179] op_sel_hi:[1,0]
	v_pk_add_f32 v[154:155], v[154:155], v[178:179] op_sel_hi:[1,0]
	v_rcp_f32_e32 v148, v148
	v_rcp_f32_e32 v149, v149
	v_rcp_f32_e32 v150, v150
	v_rcp_f32_e32 v151, v151
	v_rcp_f32_e32 v152, v152
	v_rcp_f32_e32 v153, v153
	v_rcp_f32_e32 v154, v154
	v_rcp_f32_e32 v155, v155
	s_nop 0
	v_pk_mul_f32 v[70:71], v[70:71], v[148:149]
	v_pk_mul_f32 v[72:73], v[72:73], v[150:151]
	v_pk_mul_f32 v[66:67], v[66:67], v[152:153]
	v_pk_mul_f32 v[68:69], v[68:69], v[154:155]
; __device__ __forceinline__ unsigned cvt_pk_bf16(float lo, float hi) { unsigned r; asm volatile("v_cvt_pk_bf16_f32 %0, %1, %2" : "=v"(r) : "v"(lo), "v"(hi)); return r; }
; __device__ __forceinline__ float sigmoidf_(float x) { return __builtin_amdgcn_rcpf(1.0f + __expf(-x)); }
;     __device__ __forceinline__ float rs_of(int row) const { return __builtin_amdgcn_rsqf(ss_in[row] * (1.0f / DM) + EPS); }
;     __device__ __forceinline__ void operator()(const f32x4 (&acc)[2][2][4][2], const Unit& u, int wr, int wc, int fr, int fq) const {
;     ...
; #pragma unroll
;             for (int ai = 0; ai < 2; ++ai)
; #pragma unroll
;                 for (int m = 0; m < 4; ++m) {
;                     const int row = row0 + ai * HALF + m * 16;
;                     const float s = rs_of(row);
; #pragma unroll
;                     for (int bj = 0; bj < 2; ++bj) {
;                         float v[8];
; #pragma unroll
;                         for (int n = 0; n < 2; ++n)
; #pragma unroll
;                             for (int e = 0; e < 4; ++e) { float x = acc[ai][bj][m][n][e] * s;
;                                 if (act) { const float z = 1.5957691216f * (x + 0.044715f * x * x * x); x = x * sigmoidf_(z); }
;                                 v[4 * n + e] = x; }
;                         u32x4 w; w.x = cvt_pk_bf16(v[0], v[1]); w.y = cvt_pk_bf16(v[2], v[3]); w.z = cvt_pk_bf16(v[4], v[5]); w.w = cvt_pk_bf16(v[6], v[7]);
;                         *(u32x4*)(dst + (size_t)row * ld + c0 + bj * HALF + cw) = w;
;                     }
;                 }
.Lwin_na3:
	v_cvt_pk_bf16_f32 v78, v78, v79
	v_cvt_pk_bf16_f32 v79, v80, v81
	v_cvt_pk_bf16_f32 v80, v74, v75
	v_cvt_pk_bf16_f32 v81, v76, v77
	v_cvt_pk_bf16_f32 v70, v70, v71
	v_cvt_pk_bf16_f32 v71, v72, v73
	v_cvt_pk_bf16_f32 v72, v66, v67
	v_cvt_pk_bf16_f32 v73, v68, v69
	global_store_dwordx4 v[180:181], v[78:81], off
	global_store_dwordx4 v[180:181], v[70:73], off offset:256
	v_lshl_add_u64 v[180:181], v[180:181], 0, s[10:11]
	v_pk_mul_f32 v[62:63], v[62:63], v[204:205] op_sel_hi:[1,0]
	v_pk_mul_f32 v[64:65], v[64:65], v[204:205] op_sel_hi:[1,0]
	v_pk_mul_f32 v[58:59], v[58:59], v[204:205] op_sel_hi:[1,0]
	v_pk_mul_f32 v[60:61], v[60:61], v[204:205] op_sel_hi:[1,0]
	v_pk_mul_f32 v[54:55], v[54:55], v[204:205] op_sel_hi:[1,0]
	v_pk_mul_f32 v[56:57], v[56:57], v[204:205] op_sel_hi:[1,0]
	v_pk_mul_f32 v[50:51], v[50:51], v[204:205] op_sel_hi:[1,0]
	v_pk_mul_f32 v[52:53], v[52:53], v[204:205] op_sel_hi:[1,0]
	s_cbranch_vccz .Lwin_na4
	v_pk_mul_f32 v[148:149], v[62:63], v[172:173] op_sel_hi:[1,0]
	v_pk_mul_f32 v[150:151], v[64:65], v[172:173] op_sel_hi:[1,0]
	v_pk_mul_f32 v[152:153], v[58:59], v[172:173] op_sel_hi:[1,0]
	v_pk_mul_f32 v[154:155], v[60:61], v[172:173] op_sel_hi:[1,0]
	v_pk_mul_f32 v[148:149], v[62:63], v[148:149]
	v_pk_mul_f32 v[150:151], v[64:65], v[150:151]
	v_pk_mul_f32 v[152:153], v[58:59], v[152:153]
	v_pk_mul_f32 v[154:155], v[60:61], v[154:155]
	v_pk_fma_f32 v[148:149], v[62:63], v[148:149], v[62:63]
	v_pk_fma_f32 v[150:151], v[64:65], v[150:151], v[64:65]
	v_pk_fma_f32 v[152:153], v[58:59], v[152:153], v[58:59]
	v_pk_fma_f32 v[154:155], v[60:61], v[154:155], v[60:61]
	v_pk_mul_f32 v[148:149], v[148:149], v[174:175] op_sel_hi:[1,0]
	v_pk_mul_f32 v[150:151], v[150:151], v[174:175] op_sel_hi:[1,0]
	v_pk_mul_f32 v[152:153], v[152:153], v[174:175] op_sel_hi:[1,0]
	v_pk_mul_f32 v[154:155], v[154:155], v[174:175] op_sel_hi:[1,0]
	v_pk_mul_f32 v[148:149], v[148:149], v[176:177] op_sel_hi:[1,0]
	v_pk_mul_f32 v[150:151], v[150:151], v[176:177] op_sel_hi:[1,0]
	v_pk_mul_f32 v[152:153], v[152:153], v[176:177] op_sel_hi:[1,0]
	v_pk_mul_f32 v[154:155], v[154:155], v[176:177] op_sel_hi:[1,0]
	v_exp_f32_e32 v148, v148
	v_exp_f32_e32 v149, v149
	v_exp_f32_e32 v150, v150
	v_exp_f32_e32 v151, v151
	v_exp_f32_e32 v152, v152
	v_exp_f32_e32 v153, v153
	v_exp_f32_e32 v154, v154
	v_exp_f32_e32 v155, v155
	s_nop 0
	v_pk_add_f32 v[148:149], v[148:149], v[178:179] op_sel_hi:[1,0]
	v_pk_add_f32 v[150:151], v[150:151], v[178:179] op_sel_hi:[1,0]
	v_pk_add_f32 v[152:153], v[152:153], v[178:179] op_sel_hi:[1,0]
	v_pk_add_f32 v[154:155], v[154:155], v[178:179] op_sel_hi:[1,0]
	v_rcp_f32_e32 v148, v148
	v_rcp_f32_e32 v149, v149
	v_rcp_f32_e32 v150, v150
	v_rcp_f32_e32 v151, v151
	v_rcp_f32_e32 v152, v152
	v_rcp_f32_e32 v153, v153
	v_rcp_f32_e32 v154, v154
	v_rcp_f32_e32 v155, v155
	s_nop 0
	v_pk_mul_f32 v[62:63], v[62:63], v[148:149]
	v_pk_mul_f32 v[64:65], v[64:65], v[150:151]
	v_pk_mul_f32 v[58:59], v[58:59], v[152:153]
	v_pk_mul_f32 v[60:61], v[60:61], v[154:155]
	v_pk_mul_f32 v[148:149], v[54:55], v[172:173] op_sel_hi:[1,0]
	v_pk_mul_f32 v[150:151], v[56:57], v[172:173] op_sel_hi:[1,0]
	v_pk_mul_f32 v[152:153], v[50:51], v[172:173] op_sel_hi:[1,0]
	v_pk_mul_f32 v[154:155], v[52:53], v[172:173] op_sel_hi:[1,0]
	v_pk_mul_f32 v[148:149], v[54:55], v[148:149]
	v_pk_mul_f32 v[150:151], v[56:57], v[150:151]
	v_pk_mul_f32 v[152:153], v[50:51], v[152:153]
	v_pk_mul_f32 v[154:155], v[52:53], v[154:155]
	v_pk_fma_f32 v[148:149], v[54:55], v[148:149], v[54:55]
	v_pk_fma_f32 v[150:151], v[56:57], v[150:151], v[56:57]
	v_pk_fma_f32 v[152:153], v[50:51], v[152:153], v[50:51]
	v_pk_fma_f32 v[154:155], v[52:53], v[154:155], v[52:53]
	v_pk_mul_f32 v[148:149], v[148:149], v[174:175] op_sel_hi:[1,0]
	v_pk_mul_f32 v[150:151], v[150:151], v[174:175] op_sel_hi:[1,0]
	v_pk_mul_f32 v[152:153], v[152:153], v[174:175] op_sel_hi:[1,0]
	v_pk_mul_f32 v[154:155], v[154:155], v[174:175] op_sel_hi:[1,0]
	v_pk_mul_f32 v[148:149], v[148:149], v[176:177] op_sel_hi:[1,0]
	v_pk_mul_f32 v[150:151], v[150:151], v[176:177] op_sel_hi:[1,0]
	v_pk_mul_f32 v[152:153], v[152:153], v[176:177] op_sel_hi:[1,0]
	v_pk_mul_f32 v[154:155], v[154:155], v[176:177] op_sel_hi:[1,0]
	v_exp_f32_e32 v148, v148
	v_exp_f32_e32 v149, v149
	v_exp_f32_e32 v150, v150
	v_exp_f32_e32 v151, v151
	v_exp_f32_e32 v152, v152
	v_exp_f32_e32 v153, v153
	v_exp_f32_e32 v154, v154
	v_exp_f32_e32 v155, v155
	s_nop 0
	v_pk_add_f32 v[148:149], v[148:149], v[178:179] op_sel_hi:[1,0]
	v_pk_add_f32 v[150:151], v[150:151], v[178:179] op_sel_hi:[1,0]
	v_pk_add_f32 v[152:153], v[152:153], v[178:179] op_sel_hi:[1,0]
	v_pk_add_f32 v[154:155], v[154:155], v[178:179] op_sel_hi:[1,0]
	v_rcp_f32_e32 v148, v148
	v_rcp_f32_e32 v149, v149
	v_rcp_f32_e32 v150, v150
	v_rcp_f32_e32 v151, v151
	v_rcp_f32_e32 v152, v152
	v_rcp_f32_e32 v153, v153
	v_rcp_f32_e32 v154, v154
	v_rcp_f32_e32 v155, v155
	s_nop 0
	v_pk_mul_f32 v[54:55], v[54:55], v[148:149]
	v_pk_mul_f32 v[56:57], v[56:57], v[150:151]
	v_pk_mul_f32 v[50:51], v[50:51], v[152:153]
	v_pk_mul_f32 v[52:53], v[52:53], v[154:155]
; __device__ __forceinline__ unsigned cvt_pk_bf16(float lo, float hi) { unsigned r; asm volatile("v_cvt_pk_bf16_f32 %0, %1, %2" : "=v"(r) : "v"(lo), "v"(hi)); return r; }
; __device__ __forceinline__ float sigmoidf_(float x) { return __builtin_amdgcn_rcpf(1.0f + __expf(-x)); }
;     __device__ __forceinline__ float rs_of(int row) const { return __builtin_amdgcn_rsqf(ss_in[row] * (1.0f / DM) + EPS); }
;     __device__ __forceinline__ void operator()(const f32x4 (&acc)[2][2][4][2], const Unit& u, int wr, int wc, int fr, int fq) const {
;     ...
; #pragma unroll
;             for (int ai = 0; ai < 2; ++ai)
; #pragma unroll
;                 for (int m = 0; m < 4; ++m) {
;                     const int row = row0 + ai * HALF + m * 16;
;                     const float s = rs_of(row);
; #pragma unroll
;                     for (int bj = 0; bj < 2; ++bj) {
;                         float v[8];
; #pragma unroll
;                         for (int n = 0; n < 2; ++n)
; #pragma unroll
;                             for (int e = 0; e < 4; ++e) { float x = acc[ai][bj][m][n][e] * s;
;                                 if (act) { const float z = 1.5957691216f * (x + 0.044715f * x * x * x); x = x * sigmoidf_(z); }
;                                 v[4 * n + e] = x; }
;                         u32x4 w; w.x = cvt_pk_bf16(v[0], v[1]); w.y = cvt_pk_bf16(v[2], v[3]); w.z = cvt_pk_bf16(v[4], v[5]); w.w = cvt_pk_bf16(v[6], v[7]);
;                         *(u32x4*)(dst + (size_t)row * ld + c0 + bj * HALF + cw) = w;
;                     }
;                 }
.Lwin_na4:
	v_cvt_pk_bf16_f32 v62, v62, v63
	v_cvt_pk_bf16_f32 v63, v64, v65
	v_cvt_pk_bf16_f32 v64, v58, v59
	v_cvt_pk_bf16_f32 v65, v60, v61
	v_cvt_pk_bf16_f32 v54, v54, v55
	v_cvt_pk_bf16_f32 v55, v56, v57
	v_cvt_pk_bf16_f32 v56, v50, v51
	v_cvt_pk_bf16_f32 v57, v52, v53
	global_store_dwordx4 v[180:181], v[62:65], off
	global_store_dwordx4 v[180:181], v[54:57], off offset:256
	v_lshl_add_u64 v[180:181], v[180:181], 0, s[8:9]
	v_pk_mul_f32 v[46:47], v[46:47], v[206:207] op_sel_hi:[1,0]
	v_pk_mul_f32 v[48:49], v[48:49], v[206:207] op_sel_hi:[1,0]
	v_pk_mul_f32 v[42:43], v[42:43], v[206:207] op_sel_hi:[1,0]
	v_pk_mul_f32 v[44:45], v[44:45], v[206:207] op_sel_hi:[1,0]
	v_pk_mul_f32 v[38:39], v[38:39], v[206:207] op_sel_hi:[1,0]
	v_pk_mul_f32 v[40:41], v[40:41], v[206:207] op_sel_hi:[1,0]
	v_pk_mul_f32 v[34:35], v[34:35], v[206:207] op_sel_hi:[1,0]
	v_pk_mul_f32 v[36:37], v[36:37], v[206:207] op_sel_hi:[1,0]
	s_cbranch_vccz .Lwin_na5
	v_pk_mul_f32 v[148:149], v[46:47], v[172:173] op_sel_hi:[1,0]
	v_pk_mul_f32 v[150:151], v[48:49], v[172:173] op_sel_hi:[1,0]
	v_pk_mul_f32 v[152:153], v[42:43], v[172:173] op_sel_hi:[1,0]
	v_pk_mul_f32 v[154:155], v[44:45], v[172:173] op_sel_hi:[1,0]
	v_pk_mul_f32 v[148:149], v[46:47], v[148:149]
	v_pk_mul_f32 v[150:151], v[48:49], v[150:151]
	v_pk_mul_f32 v[152:153], v[42:43], v[152:153]
	v_pk_mul_f32 v[154:155], v[44:45], v[154:155]
	v_pk_fma_f32 v[148:149], v[46:47], v[148:149], v[46:47]
	v_pk_fma_f32 v[150:151], v[48:49], v[150:151], v[48:49]
	v_pk_fma_f32 v[152:153], v[42:43], v[152:153], v[42:43]
	v_pk_fma_f32 v[154:155], v[44:45], v[154:155], v[44:45]
	v_pk_mul_f32 v[148:149], v[148:149], v[174:175] op_sel_hi:[1,0]
	v_pk_mul_f32 v[150:151], v[150:151], v[174:175] op_sel_hi:[1,0]
	v_pk_mul_f32 v[152:153], v[152:153], v[174:175] op_sel_hi:[1,0]
	v_pk_mul_f32 v[154:155], v[154:155], v[174:175] op_sel_hi:[1,0]
	v_pk_mul_f32 v[148:149], v[148:149], v[176:177] op_sel_hi:[1,0]
	v_pk_mul_f32 v[150:151], v[150:151], v[176:177] op_sel_hi:[1,0]
	v_pk_mul_f32 v[152:153], v[152:153], v[176:177] op_sel_hi:[1,0]
	v_pk_mul_f32 v[154:155], v[154:155], v[176:177] op_sel_hi:[1,0]
	v_exp_f32_e32 v148, v148
	v_exp_f32_e32 v149, v149
	v_exp_f32_e32 v150, v150
	v_exp_f32_e32 v151, v151
	v_exp_f32_e32 v152, v152
	v_exp_f32_e32 v153, v153
	v_exp_f32_e32 v154, v154
	v_exp_f32_e32 v155, v155
	s_nop 0
	v_pk_add_f32 v[148:149], v[148:149], v[178:179] op_sel_hi:[1,0]
	v_pk_add_f32 v[150:151], v[150:151], v[178:179] op_sel_hi:[1,0]
	v_pk_add_f32 v[152:153], v[152:153], v[178:179] op_sel_hi:[1,0]
	v_pk_add_f32 v[154:155], v[154:155], v[178:179] op_sel_hi:[1,0]
	v_rcp_f32_e32 v148, v148
	v_rcp_f32_e32 v149, v149
	v_rcp_f32_e32 v150, v150
	v_rcp_f32_e32 v151, v151
	v_rcp_f32_e32 v152, v152
	v_rcp_f32_e32 v153, v153
	v_rcp_f32_e32 v154, v154
	v_rcp_f32_e32 v155, v155
	s_nop 0
	v_pk_mul_f32 v[46:47], v[46:47], v[148:149]
	v_pk_mul_f32 v[48:49], v[48:49], v[150:151]
	v_pk_mul_f32 v[42:43], v[42:43], v[152:153]
	v_pk_mul_f32 v[44:45], v[44:45], v[154:155]
	v_pk_mul_f32 v[148:149], v[38:39], v[172:173] op_sel_hi:[1,0]
	v_pk_mul_f32 v[150:151], v[40:41], v[172:173] op_sel_hi:[1,0]
	v_pk_mul_f32 v[152:153], v[34:35], v[172:173] op_sel_hi:[1,0]
	v_pk_mul_f32 v[154:155], v[36:37], v[172:173] op_sel_hi:[1,0]
	v_pk_mul_f32 v[148:149], v[38:39], v[148:149]
	v_pk_mul_f32 v[150:151], v[40:41], v[150:151]
	v_pk_mul_f32 v[152:153], v[34:35], v[152:153]
	v_pk_mul_f32 v[154:155], v[36:37], v[154:155]
	v_pk_fma_f32 v[148:149], v[38:39], v[148:149], v[38:39]
	v_pk_fma_f32 v[150:151], v[40:41], v[150:151], v[40:41]
	v_pk_fma_f32 v[152:153], v[34:35], v[152:153], v[34:35]
	v_pk_fma_f32 v[154:155], v[36:37], v[154:155], v[36:37]
	v_pk_mul_f32 v[148:149], v[148:149], v[174:175] op_sel_hi:[1,0]
	v_pk_mul_f32 v[150:151], v[150:151], v[174:175] op_sel_hi:[1,0]
	v_pk_mul_f32 v[152:153], v[152:153], v[174:175] op_sel_hi:[1,0]
	v_pk_mul_f32 v[154:155], v[154:155], v[174:175] op_sel_hi:[1,0]
	v_pk_mul_f32 v[148:149], v[148:149], v[176:177] op_sel_hi:[1,0]
	v_pk_mul_f32 v[150:151], v[150:151], v[176:177] op_sel_hi:[1,0]
	v_pk_mul_f32 v[152:153], v[152:153], v[176:177] op_sel_hi:[1,0]
	v_pk_mul_f32 v[154:155], v[154:155], v[176:177] op_sel_hi:[1,0]
	v_exp_f32_e32 v148, v148
	v_exp_f32_e32 v149, v149
	v_exp_f32_e32 v150, v150
	v_exp_f32_e32 v151, v151
	v_exp_f32_e32 v152, v152
	v_exp_f32_e32 v153, v153
	v_exp_f32_e32 v154, v154
	v_exp_f32_e32 v155, v155
	s_nop 0
	v_pk_add_f32 v[148:149], v[148:149], v[178:179] op_sel_hi:[1,0]
	v_pk_add_f32 v[150:151], v[150:151], v[178:179] op_sel_hi:[1,0]
	v_pk_add_f32 v[152:153], v[152:153], v[178:179] op_sel_hi:[1,0]
	v_pk_add_f32 v[154:155], v[154:155], v[178:179] op_sel_hi:[1,0]
	v_rcp_f32_e32 v148, v148
	v_rcp_f32_e32 v149, v149
	v_rcp_f32_e32 v150, v150
	v_rcp_f32_e32 v151, v151
	v_rcp_f32_e32 v152, v152
	v_rcp_f32_e32 v153, v153
	v_rcp_f32_e32 v154, v154
	v_rcp_f32_e32 v155, v155
	s_nop 0
	v_pk_mul_f32 v[38:39], v[38:39], v[148:149]
	v_pk_mul_f32 v[40:41], v[40:41], v[150:151]
	v_pk_mul_f32 v[34:35], v[34:35], v[152:153]
	v_pk_mul_f32 v[36:37], v[36:37], v[154:155]
; __device__ __forceinline__ unsigned cvt_pk_bf16(float lo, float hi) { unsigned r; asm volatile("v_cvt_pk_bf16_f32 %0, %1, %2" : "=v"(r) : "v"(lo), "v"(hi)); return r; }
; __device__ __forceinline__ float sigmoidf_(float x) { return __builtin_amdgcn_rcpf(1.0f + __expf(-x)); }
;     __device__ __forceinline__ float rs_of(int row) const { return __builtin_amdgcn_rsqf(ss_in[row] * (1.0f / DM) + EPS); }
;     __device__ __forceinline__ void operator()(const f32x4 (&acc)[2][2][4][2], const Unit& u, int wr, int wc, int fr, int fq) const {
;     ...
; #pragma unroll
;             for (int ai = 0; ai < 2; ++ai)
; #pragma unroll
;                 for (int m = 0; m < 4; ++m) {
;                     const int row = row0 + ai * HALF + m * 16;
;                     const float s = rs_of(row);
; #pragma unroll
;                     for (int bj = 0; bj < 2; ++bj) {
;                         float v[8];
; #pragma unroll
;                         for (int n = 0; n < 2; ++n)
; #pragma unroll
;                             for (int e = 0; e < 4; ++e) { float x = acc[ai][bj][m][n][e] * s;
;                                 if (act) { const float z = 1.5957691216f * (x + 0.044715f * x * x * x); x = x * sigmoidf_(z); }
;                                 v[4 * n + e] = x; }
;                         u32x4 w; w.x = cvt_pk_bf16(v[0], v[1]); w.y = cvt_pk_bf16(v[2], v[3]); w.z = cvt_pk_bf16(v[4], v[5]); w.w = cvt_pk_bf16(v[6], v[7]);
;                         *(u32x4*)(dst + (size_t)row * ld + c0 + bj * HALF + cw) = w;
;                     }
;                 }
.Lwin_na5:
	v_cvt_pk_bf16_f32 v46, v46, v47
	v_cvt_pk_bf16_f32 v47, v48, v49
	v_cvt_pk_bf16_f32 v48, v42, v43
	v_cvt_pk_bf16_f32 v49, v44, v45
	v_cvt_pk_bf16_f32 v38, v38, v39
	v_cvt_pk_bf16_f32 v39, v40, v41
	v_cvt_pk_bf16_f32 v40, v34, v35
	v_cvt_pk_bf16_f32 v41, v36, v37
	global_store_dwordx4 v[180:181], v[46:49], off
	global_store_dwordx4 v[180:181], v[38:41], off offset:256
	v_lshl_add_u64 v[180:181], v[180:181], 0, s[8:9]
	v_pk_mul_f32 v[30:31], v[30:31], v[208:209] op_sel_hi:[1,0]
	v_pk_mul_f32 v[32:33], v[32:33], v[208:209] op_sel_hi:[1,0]
	v_pk_mul_f32 v[26:27], v[26:27], v[208:209] op_sel_hi:[1,0]
	v_pk_mul_f32 v[28:29], v[28:29], v[208:209] op_sel_hi:[1,0]
	v_pk_mul_f32 v[22:23], v[22:23], v[208:209] op_sel_hi:[1,0]
	v_pk_mul_f32 v[24:25], v[24:25], v[208:209] op_sel_hi:[1,0]
	v_pk_mul_f32 v[18:19], v[18:19], v[208:209] op_sel_hi:[1,0]
	v_pk_mul_f32 v[20:21], v[20:21], v[208:209] op_sel_hi:[1,0]
	s_cbranch_vccz .Lwin_na6
	v_pk_mul_f32 v[148:149], v[30:31], v[172:173] op_sel_hi:[1,0]
	v_pk_mul_f32 v[150:151], v[32:33], v[172:173] op_sel_hi:[1,0]
	v_pk_mul_f32 v[152:153], v[26:27], v[172:173] op_sel_hi:[1,0]
	v_pk_mul_f32 v[154:155], v[28:29], v[172:173] op_sel_hi:[1,0]
	v_pk_mul_f32 v[148:149], v[30:31], v[148:149]
	v_pk_mul_f32 v[150:151], v[32:33], v[150:151]
	v_pk_mul_f32 v[152:153], v[26:27], v[152:153]
	v_pk_mul_f32 v[154:155], v[28:29], v[154:155]
	v_pk_fma_f32 v[148:149], v[30:31], v[148:149], v[30:31]
	v_pk_fma_f32 v[150:151], v[32:33], v[150:151], v[32:33]
	v_pk_fma_f32 v[152:153], v[26:27], v[152:153], v[26:27]
	v_pk_fma_f32 v[154:155], v[28:29], v[154:155], v[28:29]
	v_pk_mul_f32 v[148:149], v[148:149], v[174:175] op_sel_hi:[1,0]
	v_pk_mul_f32 v[150:151], v[150:151], v[174:175] op_sel_hi:[1,0]
	v_pk_mul_f32 v[152:153], v[152:153], v[174:175] op_sel_hi:[1,0]
	v_pk_mul_f32 v[154:155], v[154:155], v[174:175] op_sel_hi:[1,0]
	v_pk_mul_f32 v[148:149], v[148:149], v[176:177] op_sel_hi:[1,0]
	v_pk_mul_f32 v[150:151], v[150:151], v[176:177] op_sel_hi:[1,0]
	v_pk_mul_f32 v[152:153], v[152:153], v[176:177] op_sel_hi:[1,0]
	v_pk_mul_f32 v[154:155], v[154:155], v[176:177] op_sel_hi:[1,0]
	v_exp_f32_e32 v148, v148
	v_exp_f32_e32 v149, v149
	v_exp_f32_e32 v150, v150
	v_exp_f32_e32 v151, v151
	v_exp_f32_e32 v152, v152
	v_exp_f32_e32 v153, v153
	v_exp_f32_e32 v154, v154
	v_exp_f32_e32 v155, v155
	s_nop 0
	v_pk_add_f32 v[148:149], v[148:149], v[178:179] op_sel_hi:[1,0]
	v_pk_add_f32 v[150:151], v[150:151], v[178:179] op_sel_hi:[1,0]
	v_pk_add_f32 v[152:153], v[152:153], v[178:179] op_sel_hi:[1,0]
	v_pk_add_f32 v[154:155], v[154:155], v[178:179] op_sel_hi:[1,0]
	v_rcp_f32_e32 v148, v148
	v_rcp_f32_e32 v149, v149
	v_rcp_f32_e32 v150, v150
	v_rcp_f32_e32 v151, v151
	v_rcp_f32_e32 v152, v152
	v_rcp_f32_e32 v153, v153
	v_rcp_f32_e32 v154, v154
	v_rcp_f32_e32 v155, v155
	s_nop 0
	v_pk_mul_f32 v[30:31], v[30:31], v[148:149]
	v_pk_mul_f32 v[32:33], v[32:33], v[150:151]
	v_pk_mul_f32 v[26:27], v[26:27], v[152:153]
	v_pk_mul_f32 v[28:29], v[28:29], v[154:155]
	v_pk_mul_f32 v[148:149], v[22:23], v[172:173] op_sel_hi:[1,0]
	v_pk_mul_f32 v[150:151], v[24:25], v[172:173] op_sel_hi:[1,0]
	v_pk_mul_f32 v[152:153], v[18:19], v[172:173] op_sel_hi:[1,0]
	v_pk_mul_f32 v[154:155], v[20:21], v[172:173] op_sel_hi:[1,0]
	v_pk_mul_f32 v[148:149], v[22:23], v[148:149]
	v_pk_mul_f32 v[150:151], v[24:25], v[150:151]
	v_pk_mul_f32 v[152:153], v[18:19], v[152:153]
	v_pk_mul_f32 v[154:155], v[20:21], v[154:155]
	v_pk_fma_f32 v[148:149], v[22:23], v[148:149], v[22:23]
	v_pk_fma_f32 v[150:151], v[24:25], v[150:151], v[24:25]
	v_pk_fma_f32 v[152:153], v[18:19], v[152:153], v[18:19]
	v_pk_fma_f32 v[154:155], v[20:21], v[154:155], v[20:21]
	v_pk_mul_f32 v[148:149], v[148:149], v[174:175] op_sel_hi:[1,0]
	v_pk_mul_f32 v[150:151], v[150:151], v[174:175] op_sel_hi:[1,0]
	v_pk_mul_f32 v[152:153], v[152:153], v[174:175] op_sel_hi:[1,0]
	v_pk_mul_f32 v[154:155], v[154:155], v[174:175] op_sel_hi:[1,0]
	v_pk_mul_f32 v[148:149], v[148:149], v[176:177] op_sel_hi:[1,0]
	v_pk_mul_f32 v[150:151], v[150:151], v[176:177] op_sel_hi:[1,0]
	v_pk_mul_f32 v[152:153], v[152:153], v[176:177] op_sel_hi:[1,0]
	v_pk_mul_f32 v[154:155], v[154:155], v[176:177] op_sel_hi:[1,0]
	v_exp_f32_e32 v148, v148
	v_exp_f32_e32 v149, v149
	v_exp_f32_e32 v150, v150
	v_exp_f32_e32 v151, v151
	v_exp_f32_e32 v152, v152
	v_exp_f32_e32 v153, v153
	v_exp_f32_e32 v154, v154
	v_exp_f32_e32 v155, v155
	s_nop 0
	v_pk_add_f32 v[148:149], v[148:149], v[178:179] op_sel_hi:[1,0]
	v_pk_add_f32 v[150:151], v[150:151], v[178:179] op_sel_hi:[1,0]
	v_pk_add_f32 v[152:153], v[152:153], v[178:179] op_sel_hi:[1,0]
	v_pk_add_f32 v[154:155], v[154:155], v[178:179] op_sel_hi:[1,0]
	v_rcp_f32_e32 v148, v148
	v_rcp_f32_e32 v149, v149
	v_rcp_f32_e32 v150, v150
	v_rcp_f32_e32 v151, v151
	v_rcp_f32_e32 v152, v152
	v_rcp_f32_e32 v153, v153
	v_rcp_f32_e32 v154, v154
	v_rcp_f32_e32 v155, v155
	s_nop 0
	v_pk_mul_f32 v[22:23], v[22:23], v[148:149]
	v_pk_mul_f32 v[24:25], v[24:25], v[150:151]
	v_pk_mul_f32 v[18:19], v[18:19], v[152:153]
	v_pk_mul_f32 v[20:21], v[20:21], v[154:155]
; __device__ __forceinline__ unsigned cvt_pk_bf16(float lo, float hi) { unsigned r; asm volatile("v_cvt_pk_bf16_f32 %0, %1, %2" : "=v"(r) : "v"(lo), "v"(hi)); return r; }
; __device__ __forceinline__ float sigmoidf_(float x) { return __builtin_amdgcn_rcpf(1.0f + __expf(-x)); }
;     __device__ __forceinline__ float rs_of(int row) const { return __builtin_amdgcn_rsqf(ss_in[row] * (1.0f / DM) + EPS); }
; #define PG8_BAR __builtin_amdgcn_s_barrier()
;     __device__ __forceinline__ void operator()(const f32x4 (&acc)[2][2][4][2], const Unit& u, int wr, int wc, int fr, int fq) const {
;     ...
; #pragma unroll
;             for (int ai = 0; ai < 2; ++ai)
; #pragma unroll
;                 for (int m = 0; m < 4; ++m) {
;                     const int row = row0 + ai * HALF + m * 16;
;                     const float s = rs_of(row);
; #pragma unroll
;                     for (int bj = 0; bj < 2; ++bj) {
;                         float v[8];
; #pragma unroll
;                         for (int n = 0; n < 2; ++n)
; #pragma unroll
;                             for (int e = 0; e < 4; ++e) { float x = acc[ai][bj][m][n][e] * s;
;                                 if (act) { const float z = 1.5957691216f * (x + 0.044715f * x * x * x); x = x * sigmoidf_(z); }
;                                 v[4 * n + e] = x; }
;                         u32x4 w; w.x = cvt_pk_bf16(v[0], v[1]); w.y = cvt_pk_bf16(v[2], v[3]); w.z = cvt_pk_bf16(v[4], v[5]); w.w = cvt_pk_bf16(v[6], v[7]);
;                         *(u32x4*)(dst + (size_t)row * ld + c0 + bj * HALF + cw) = w;
;                     }
;                 }
; template <class Epi> __device__ __forceinline__ void gemm_phase(LAS unsigned char* lds, const Gemm g, const StaticOrder& S, const Epi& E, const int tid) {
;     ...
;         if (wr == 0) PG8_BAR;
;         E(acc, cur, wr, wc, fr, fq);
;         if (!has_next) break;
.Lwin_na6:
	v_cvt_pk_bf16_f32 v30, v30, v31
	v_cvt_pk_bf16_f32 v31, v32, v33
	v_cvt_pk_bf16_f32 v32, v26, v27
	v_cvt_pk_bf16_f32 v33, v28, v29
	v_cvt_pk_bf16_f32 v22, v22, v23
	v_cvt_pk_bf16_f32 v23, v24, v25
	v_cvt_pk_bf16_f32 v24, v18, v19
	v_cvt_pk_bf16_f32 v25, v20, v21
	global_store_dwordx4 v[180:181], v[30:33], off
	global_store_dwordx4 v[180:181], v[22:25], off offset:256
	v_lshl_add_u64 v[180:181], v[180:181], 0, s[8:9]
	v_pk_mul_f32 v[14:15], v[14:15], v[210:211] op_sel_hi:[1,0]
	v_pk_mul_f32 v[16:17], v[16:17], v[210:211] op_sel_hi:[1,0]
	v_pk_mul_f32 v[10:11], v[10:11], v[210:211] op_sel_hi:[1,0]
	v_pk_mul_f32 v[12:13], v[12:13], v[210:211] op_sel_hi:[1,0]
	v_pk_mul_f32 v[6:7], v[6:7], v[210:211] op_sel_hi:[1,0]
	v_pk_mul_f32 v[8:9], v[8:9], v[210:211] op_sel_hi:[1,0]
	v_pk_mul_f32 v[2:3], v[2:3], v[210:211] op_sel_hi:[1,0]
	v_pk_mul_f32 v[4:5], v[4:5], v[210:211] op_sel_hi:[1,0]
	s_cbranch_vccz .Lwin_na7
	v_pk_mul_f32 v[148:149], v[14:15], v[172:173] op_sel_hi:[1,0]
	v_pk_mul_f32 v[150:151], v[16:17], v[172:173] op_sel_hi:[1,0]
	v_pk_mul_f32 v[152:153], v[10:11], v[172:173] op_sel_hi:[1,0]
	v_pk_mul_f32 v[154:155], v[12:13], v[172:173] op_sel_hi:[1,0]
	v_pk_mul_f32 v[148:149], v[14:15], v[148:149]
	v_pk_mul_f32 v[150:151], v[16:17], v[150:151]
	v_pk_mul_f32 v[152:153], v[10:11], v[152:153]
	v_pk_mul_f32 v[154:155], v[12:13], v[154:155]
	v_pk_fma_f32 v[148:149], v[14:15], v[148:149], v[14:15]
	v_pk_fma_f32 v[150:151], v[16:17], v[150:151], v[16:17]
	v_pk_fma_f32 v[152:153], v[10:11], v[152:153], v[10:11]
	v_pk_fma_f32 v[154:155], v[12:13], v[154:155], v[12:13]
	v_pk_mul_f32 v[148:149], v[148:149], v[174:175] op_sel_hi:[1,0]
	v_pk_mul_f32 v[150:151], v[150:151], v[174:175] op_sel_hi:[1,0]
	v_pk_mul_f32 v[152:153], v[152:153], v[174:175] op_sel_hi:[1,0]
	v_pk_mul_f32 v[154:155], v[154:155], v[174:175] op_sel_hi:[1,0]
	v_pk_mul_f32 v[148:149], v[148:149], v[176:177] op_sel_hi:[1,0]
	v_pk_mul_f32 v[150:151], v[150:151], v[176:177] op_sel_hi:[1,0]
	v_pk_mul_f32 v[152:153], v[152:153], v[176:177] op_sel_hi:[1,0]
	v_pk_mul_f32 v[154:155], v[154:155], v[176:177] op_sel_hi:[1,0]
	v_exp_f32_e32 v148, v148
	v_exp_f32_e32 v149, v149
	v_exp_f32_e32 v150, v150
	v_exp_f32_e32 v151, v151
	v_exp_f32_e32 v152, v152
	v_exp_f32_e32 v153, v153
	v_exp_f32_e32 v154, v154
	v_exp_f32_e32 v155, v155
	s_nop 0
	v_pk_add_f32 v[148:149], v[148:149], v[178:179] op_sel_hi:[1,0]
	v_pk_add_f32 v[150:151], v[150:151], v[178:179] op_sel_hi:[1,0]
	v_pk_add_f32 v[152:153], v[152:153], v[178:179] op_sel_hi:[1,0]
	v_pk_add_f32 v[154:155], v[154:155], v[178:179] op_sel_hi:[1,0]
	v_rcp_f32_e32 v148, v148
	v_rcp_f32_e32 v149, v149
	v_rcp_f32_e32 v150, v150
	v_rcp_f32_e32 v151, v151
	v_rcp_f32_e32 v152, v152
	v_rcp_f32_e32 v153, v153
	v_rcp_f32_e32 v154, v154
	v_rcp_f32_e32 v155, v155
	s_nop 0
	v_pk_mul_f32 v[14:15], v[14:15], v[148:149]
	v_pk_mul_f32 v[16:17], v[16:17], v[150:151]
	v_pk_mul_f32 v[10:11], v[10:11], v[152:153]
	v_pk_mul_f32 v[12:13], v[12:13], v[154:155]
	v_pk_mul_f32 v[148:149], v[6:7], v[172:173] op_sel_hi:[1,0]
	v_pk_mul_f32 v[150:151], v[8:9], v[172:173] op_sel_hi:[1,0]
	v_pk_mul_f32 v[152:153], v[2:3], v[172:173] op_sel_hi:[1,0]
	v_pk_mul_f32 v[154:155], v[4:5], v[172:173] op_sel_hi:[1,0]
	v_pk_mul_f32 v[148:149], v[6:7], v[148:149]
	v_pk_mul_f32 v[150:151], v[8:9], v[150:151]
	v_pk_mul_f32 v[152:153], v[2:3], v[152:153]
	v_pk_mul_f32 v[154:155], v[4:5], v[154:155]
	v_pk_fma_f32 v[148:149], v[6:7], v[148:149], v[6:7]
	v_pk_fma_f32 v[150:151], v[8:9], v[150:151], v[8:9]
	v_pk_fma_f32 v[152:153], v[2:3], v[152:153], v[2:3]
	v_pk_fma_f32 v[154:155], v[4:5], v[154:155], v[4:5]
	v_pk_mul_f32 v[148:149], v[148:149], v[174:175] op_sel_hi:[1,0]
	v_pk_mul_f32 v[150:151], v[150:151], v[174:175] op_sel_hi:[1,0]
	v_pk_mul_f32 v[152:153], v[152:153], v[174:175] op_sel_hi:[1,0]
	v_pk_mul_f32 v[154:155], v[154:155], v[174:175] op_sel_hi:[1,0]
	v_pk_mul_f32 v[148:149], v[148:149], v[176:177] op_sel_hi:[1,0]
	v_pk_mul_f32 v[150:151], v[150:151], v[176:177] op_sel_hi:[1,0]
	v_pk_mul_f32 v[152:153], v[152:153], v[176:177] op_sel_hi:[1,0]
	v_pk_mul_f32 v[154:155], v[154:155], v[176:177] op_sel_hi:[1,0]
	v_exp_f32_e32 v148, v148
	v_exp_f32_e32 v149, v149
	v_exp_f32_e32 v150, v150
	v_exp_f32_e32 v151, v151
	v_exp_f32_e32 v152, v152
	v_exp_f32_e32 v153, v153
	v_exp_f32_e32 v154, v154
	v_exp_f32_e32 v155, v155
	s_nop 0
	v_pk_add_f32 v[148:149], v[148:149], v[178:179] op_sel_hi:[1,0]
	v_pk_add_f32 v[150:151], v[150:151], v[178:179] op_sel_hi:[1,0]
	v_pk_add_f32 v[152:153], v[152:153], v[178:179] op_sel_hi:[1,0]
	v_pk_add_f32 v[154:155], v[154:155], v[178:179] op_sel_hi:[1,0]
	v_rcp_f32_e32 v148, v148
	v_rcp_f32_e32 v149, v149
	v_rcp_f32_e32 v150, v150
	v_rcp_f32_e32 v151, v151
	v_rcp_f32_e32 v152, v152
	v_rcp_f32_e32 v153, v153
	v_rcp_f32_e32 v154, v154
	v_rcp_f32_e32 v155, v155
	s_nop 0
	v_pk_mul_f32 v[6:7], v[6:7], v[148:149]
	v_pk_mul_f32 v[8:9], v[8:9], v[150:151]
	v_pk_mul_f32 v[2:3], v[2:3], v[152:153]
	v_pk_mul_f32 v[4:5], v[4:5], v[154:155]
.Lwin_na7:
	v_cvt_pk_bf16_f32 v14, v14, v15
	v_cvt_pk_bf16_f32 v15, v16, v17
	v_cvt_pk_bf16_f32 v16, v10, v11
	v_cvt_pk_bf16_f32 v17, v12, v13
	v_cvt_pk_bf16_f32 v6, v6, v7
	v_cvt_pk_bf16_f32 v7, v8, v9
	v_cvt_pk_bf16_f32 v8, v2, v3
	v_cvt_pk_bf16_f32 v9, v4, v5
	global_store_dwordx4 v[180:181], v[14:17], off
	global_store_dwordx4 v[180:181], v[6:9], off offset:256
	s_andn2_b64 vcc, exec, s[40:41]
	s_mov_b64 s[4:5], -1
	s_cbranch_vccnz .LBB0_235
	s_andn2_b64 vcc, exec, s[72:73]
	s_cbranch_vccnz .LBB0_234
	s_barrier
	s_branch .LBB0_234
